# grid barrier: XCD leader publishes per-XCD generation word after one L2 writeback; every workgroup polls the sixteen generation words directly (no cross-XCD arrival counter hop)
# speedup vs baseline: 1.0133x; 1.0053x over previous
.Lgb_q2_s0:
	s_add_i32 s17, s16, 1
	s_cmp_eq_u32 s17, s12
	s_cbranch_scc0 .Lgb_wait_s0
	buffer_wbl2 sc1
	s_waitcnt vmcnt(0)
	v_mov_b32_e32 v0, 0x2000
	global_atomic_add v0, v6, s[6:7] offset:1024
.Lgb_wait_s0:
	s_add_u32 s6, s2, 0x6400
	s_addc_u32 s7, s3, 0
	s_add_i32 s15, s15, 1
	s_mov_b64 exec, 0xffff
	v_lshlrev_b32_e32 v0, 8, v217
	v_mov_b32_e32 v6, s15
	s_mov_b32 s18, 0
.Lgb_spin_s0:
	global_load_dword v7, v0, s[6:7] sc1
	s_add_u32 s18, s18, 1
	s_waitcnt vmcnt(0)
	v_sub_u32_e32 v7, v7, v6
	v_cmp_lt_i32_e32 vcc, -1, v7
	s_nop 1
	s_bcnt1_i32_b64 s17, vcc
	s_cmp_ge_u32 s17, s13
	s_cbranch_scc1 .Lgb_acq_s0
	s_sleep 1
	s_cmp_lt_u32 s18, 0x10000
	s_cbranch_scc1 .Lgb_spin_s0

.Lgb_q2_s1:
	s_add_i32 s19, s18, 1
	s_cmp_eq_u32 s19, s12
	s_cbranch_scc0 .Lgb_wait_s1
	buffer_wbl2 sc1
	s_waitcnt vmcnt(0)
	v_mov_b32_e32 v0, 0x2000
	global_atomic_add v0, v6, s[6:7] offset:1024
.Lgb_wait_s1:
	s_add_u32 s6, s2, 0x6400
	s_addc_u32 s7, s3, 0
	s_add_i32 s17, s17, 1
	s_mov_b64 exec, 0xffff
	v_lshlrev_b32_e32 v0, 8, v217
	v_mov_b32_e32 v6, s17
	s_mov_b32 s20, 0
.Lgb_spin_s1:
	global_load_dword v7, v0, s[6:7] sc1
	s_add_u32 s20, s20, 1
	s_waitcnt vmcnt(0)
	v_sub_u32_e32 v7, v7, v6
	v_cmp_lt_i32_e32 vcc, -1, v7
	s_nop 1
	s_bcnt1_i32_b64 s19, vcc
	s_cmp_ge_u32 s19, s13
	s_cbranch_scc1 .Lgb_acq_s1
	s_sleep 1
	s_cmp_lt_u32 s20, 0x10000
	s_cbranch_scc1 .Lgb_spin_s1

.Lgb_q2_s2:
	s_add_i32 s15, s14, 1
	s_cmp_eq_u32 s15, s10
	s_cbranch_scc0 .Lgb_wait_s2
	buffer_wbl2 sc1
	s_waitcnt vmcnt(0)
	v_mov_b32_e32 v0, 0x2000
	global_atomic_add v0, v6, s[6:7] offset:1024
.Lgb_wait_s2:
	s_add_u32 s6, s4, 0x6400
	s_addc_u32 s7, s5, 0
	s_add_i32 s13, s13, 1
	s_mov_b64 exec, 0xffff
	v_lshlrev_b32_e32 v0, 8, v217
	v_mov_b32_e32 v6, s13
	s_mov_b32 s18, 0
.Lgb_spin_s2:
	global_load_dword v7, v0, s[6:7] sc1
	s_add_u32 s18, s18, 1
	s_waitcnt vmcnt(0)
	v_sub_u32_e32 v7, v7, v6
	v_cmp_lt_i32_e32 vcc, -1, v7
	s_nop 1
	s_bcnt1_i32_b64 s15, vcc
	s_cmp_ge_u32 s15, s11
	s_cbranch_scc1 .Lgb_acq_s2
	s_sleep 1
	s_cmp_lt_u32 s18, 0x10000
	s_cbranch_scc1 .Lgb_spin_s2

.Lgb_q2_s3:
	s_add_i32 s13, s12, 1
	s_cmp_eq_u32 s13, s7
	s_cbranch_scc0 .Lgb_wait_s3
	buffer_wbl2 sc1
	s_waitcnt vmcnt(0)
	v_mov_b32_e32 v0, 0x2000
	global_atomic_add v0, v6, s[4:5] offset:1024
.Lgb_wait_s3:
	s_add_u32 s4, s2, 0x6400
	s_addc_u32 s5, s3, 0
	s_add_i32 s11, s11, 1
	s_mov_b64 exec, 0xffff
	v_lshlrev_b32_e32 v0, 8, v217
	v_mov_b32_e32 v6, s11
	s_mov_b32 s14, 0
.Lgb_spin_s3:
	global_load_dword v7, v0, s[4:5] sc1
	s_add_u32 s14, s14, 1
	s_waitcnt vmcnt(0)
	v_sub_u32_e32 v7, v7, v6
	v_cmp_lt_i32_e32 vcc, -1, v7
	s_nop 1
	s_bcnt1_i32_b64 s13, vcc
	s_cmp_ge_u32 s13, s9
	s_cbranch_scc1 .Lgb_acq_s3
	s_sleep 1
	s_cmp_lt_u32 s14, 0x10000
	s_cbranch_scc1 .Lgb_spin_s3

.Lgb_q2_s4:
	s_add_i32 s12, s11, 1
	s_cmp_eq_u32 s12, s7
	s_cbranch_scc0 .Lgb_wait_s4
	buffer_wbl2 sc1
	s_waitcnt vmcnt(0)
	v_mov_b32_e32 v0, 0x2000
	global_atomic_add v0, v3, s[4:5] offset:1024
.Lgb_wait_s4:
	s_add_u32 s4, s2, 0x6400
	s_addc_u32 s5, s3, 0
	s_add_i32 s10, s10, 1
	s_mov_b64 exec, 0xffff
	v_lshlrev_b32_e32 v0, 8, v217
	v_mov_b32_e32 v3, s10
	s_mov_b32 s13, 0
.Lgb_spin_s4:
	global_load_dword v6, v0, s[4:5] sc1
	s_add_u32 s13, s13, 1
	s_waitcnt vmcnt(0)
	v_sub_u32_e32 v6, v6, v3
	v_cmp_lt_i32_e32 vcc, -1, v6
	s_nop 1
	s_bcnt1_i32_b64 s12, vcc
	s_cmp_ge_u32 s12, s8
	s_cbranch_scc1 .Lgb_acq_s4
	s_sleep 1
	s_cmp_lt_u32 s13, 0x10000
	s_cbranch_scc1 .Lgb_spin_s4

.Lgb_q2_s5:
	s_add_i32 s12, s11, 1
	s_cmp_eq_u32 s12, s7
	s_cbranch_scc0 .Lgb_wait_s5
	buffer_wbl2 sc1
	s_waitcnt vmcnt(0)
	v_mov_b32_e32 v0, 0x2000
	global_atomic_add v0, v6, s[4:5] offset:1024
.Lgb_wait_s5:
	s_add_u32 s4, s2, 0x6400
	s_addc_u32 s5, s3, 0
	s_add_i32 s10, s10, 1
	s_mov_b64 exec, 0xffff
	v_lshlrev_b32_e32 v0, 8, v217
	v_mov_b32_e32 v6, s10
	s_mov_b32 s13, 0
.Lgb_spin_s5:
	global_load_dword v7, v0, s[4:5] sc1
	s_add_u32 s13, s13, 1
	s_waitcnt vmcnt(0)
	v_sub_u32_e32 v7, v7, v6
	v_cmp_lt_i32_e32 vcc, -1, v7
	s_nop 1
	s_bcnt1_i32_b64 s12, vcc
	s_cmp_ge_u32 s12, s8
	s_cbranch_scc1 .Lgb_acq_s5
	s_sleep 1
	s_cmp_lt_u32 s13, 0x10000
	s_cbranch_scc1 .Lgb_spin_s5

.Lgb_q2_s6:
	s_add_i32 s15, s14, 1
	s_cmp_eq_u32 s15, s10
	s_cbranch_scc0 .Lgb_wait_s6
	buffer_wbl2 sc1
	s_waitcnt vmcnt(0)
	v_mov_b32_e32 v0, 0x2000
	global_atomic_add v0, v6, s[4:5] offset:1024
.Lgb_wait_s6:
	s_add_u32 s4, s2, 0x6400
	s_addc_u32 s5, s3, 0
	s_add_i32 s13, s13, 1
	s_mov_b64 exec, 0xffff
	v_lshlrev_b32_e32 v0, 8, v217
	v_mov_b32_e32 v6, s13
	s_mov_b32 s18, 0
.Lgb_spin_s6:
	global_load_dword v7, v0, s[4:5] sc1
	s_add_u32 s18, s18, 1
	s_waitcnt vmcnt(0)
	v_sub_u32_e32 v7, v7, v6
	v_cmp_lt_i32_e32 vcc, -1, v7
	s_nop 1
	s_bcnt1_i32_b64 s15, vcc
	s_cmp_ge_u32 s15, s11
	s_cbranch_scc1 .Lgb_acq_s6
	s_sleep 1
	s_cmp_lt_u32 s18, 0x10000
	s_cbranch_scc1 .Lgb_spin_s6
